# one static s_setprio 1 for waves 4-7 during the attention prompt units (reset for sample units and at phase exit)
# speedup vs baseline: 1.0594x; 1.0012x over previous
; #define LAS __attribute__((address_space(3)))
; #define WAIT_R2(N, R) asm volatile("s_waitcnt vmcnt(" #N ")" : "+v"(R.k[0]), "+v"(R.k[1]), "+v"(R.k[2]), "+v"(R.k[3]), "+v"(R.v[0]), "+v"(R.v[1]), "+v"(R.v[2]), "+v"(R.v[3]), "+v"(R.ck))
; #define SSTEP(tt, RR) do { WAIT_R2(27, RR); sstore2(RR, lds + (((tt) + 1) & 1) * AT_BUF, true, st); sload2a(RR, a, b, h, (27 - (tt)) > 0 ? 27 - (tt) : 0, cbase, st); __syncthreads(); } while (0)
; __device__ __forceinline__ void attn_unit_sample(const Args& a, LAS unsigned char* lds, int b, int h) {
;     int tid_ = threadIdx.x; asm volatile("" : "+v"(tid_));
;     const int tid = tid_, lane = tid & 63, w = __builtin_amdgcn_readfirstlane(tid >> 6), l31 = lane & 31, hi = lane >> 5;
;     const float* cbase = (const float*)(a.ws + WS_CS) + (size_t)(b * 16 + h) * 2112;
;     if (w >= 2 && w < 6) {
;         const int st = tid - 128;
;         TileRegs2 R0, R1, R2, R3;
;         sload2(R0, a, b, h, 32, cbase, st); sload2a(R1, a, b, h, 31, cbase, st); sload2a(R2, a, b, h, 30, cbase, st); sload2a(R3, a, b, h, 29, cbase, st);
;         sstore2(R0, lds, false, st);
;         sload2a(R0, a, b, h, 28, cbase, st);
;         __syncthreads();
;     ...
; #pragma unroll 1
;         for (int t = 0; t < 32; t += 4) { SSTEP(t, R1); SSTEP(t + 1, R2); SSTEP(t + 2, R3); SSTEP(t + 3, R0); }
;         SSTEP(32, R1);
;     ...
;         WAIT_R2(0, R0); WAIT_R2(0, R1); WAIT_R2(0, R2); WAIT_R2(0, R3);
;     } else {
;         const bool active = w < 2;
;         const int qpos = 2048 + 32 * (w & 1) + l31;
;         const size_t qrow = (size_t)(MP + b * 64 + 32 * (w & 1) + l31);
;         const bf16_t* qkv = (const bf16_t*)(a.ws + WS_PROJ);
;         bf16x8 qf[4];
; #pragma unroll
;         for (int ks = 0; ks < 4; ++ks) qf[ks] = *(const bf16x8*)(qkv + qrow * NPJ + h * 64 + 16 * ks + 8 * hi);
;         const float cq2 = cbase[qpos] * LOG2E;
;         float mrun = -INFINITY, lrun = 0.f;
;         f32x16 ot[2]; ot[0] = f32x16{}; ot[1] = f32x16{};
;         __syncthreads();
.LBB0_1646:
	s_setprio 0
	v_mov_b32_e32 v106, v0
	s_ashr_i32 s0, s56, 4
	v_readfirstlane_b32 s1, v106
	s_and_b32 s57, s56, 15
	s_ashr_i32 s58, s1, 6
	s_mul_i32 s14, s56, 0x2100
	s_mul_hi_i32 s1, s56, 0x2100
	s_add_u32 s70, s63, s14
	s_addc_u32 s71, s78, s1
	s_add_i32 s1, s58, -2
	s_cmp_gt_u32 s1, 3
	s_mov_b64 s[72:73], -1
	s_cbranch_scc0 .LBB0_1660
	s_lshl_b32 s1, s58, 5
	s_and_b32 s1, s1, 32
	s_lshl_b32 s14, s0, 6
	s_or_b32 s14, s14, s1
	v_and_b32_e32 v107, 31, v106
	s_addk_i32 s14, 0x4000
	v_or_b32_e32 v104, s14, v107
	s_waitcnt lgkmcnt(0)
	v_mov_b64_e32 v[2:3], s[26:27]
	v_bfe_u32 v6, v106, 5, 1
	v_mad_i64_i32 v[2:3], s[72:73], v104, s81, v[2:3]
	s_lshl_b32 s14, s57, 7
	v_lshl_add_u64 v[2:3], v[2:3], 0, s[14:15]
	v_lshlrev_b32_e32 v66, 4, v6
	v_or_b32_e32 v108, s1, v107
	v_lshl_add_u64 v[2:3], v[2:3], 0, v[66:67]
	v_lshlrev_b32_e32 v66, 2, v108
	v_lshl_add_u64 v[4:5], s[70:71], 0, v[66:67]
	v_add_co_u32_e32 v4, vcc, s82, v4
	s_lshl_b32 s1, s57, 6
	s_nop 0
	v_addc_co_u32_e32 v5, vcc, 0, v5, vcc
	global_load_dword v4, v[4:5], off
	s_nop 0
	global_load_dwordx4 v[88:91], v[2:3], off
	global_load_dwordx4 v[92:95], v[2:3], off offset:32
	global_load_dwordx4 v[96:99], v[2:3], off offset:64
	global_load_dwordx4 v[100:103], v[2:3], off offset:96
	v_mov_b32_e32 v64, v67
	v_mov_b32_e32 v65, v67
	v_lshlrev_b32_e32 v110, 3, v6
	v_add_u32_e32 v111, -1, v6
	v_lshlrev_b32_e32 v109, 2, v6
	s_cmp_lt_i32 s58, 2
	v_mov_b32_e32 v66, v67
	v_mov_b32_e32 v68, v67
	v_mov_b32_e32 v69, v67
	v_mov_b32_e32 v70, v67
	v_mov_b32_e32 v71, v67
	v_mov_b32_e32 v72, v67
	v_mov_b32_e32 v73, v67
	v_mov_b32_e32 v74, v67
	v_mov_b32_e32 v75, v67
	v_mov_b32_e32 v76, v67
	v_mov_b32_e32 v77, v67
	v_mov_b32_e32 v78, v67
	v_mov_b32_e32 v79, v67
	v_mov_b64_e32 v[18:19], v[64:65]
	s_mov_b32 s14, 0
	v_mov_b32_e32 v86, v67
	v_mov_b32_e32 v87, v67
	v_mul_u32_u24_e32 v112, 0x90, v107
	v_mad_u32_u24 v113, v107, s83, v148
	v_mul_u32_u24_e32 v114, 0x88, v107
	v_and_b32_e32 v84, 0x3f803f80, v111
	v_and_b32_e32 v85, 0x3f80, v111
	v_or_b32_e32 v115, 32, v109
	v_or_b32_e32 v116, 33, v109
	v_or_b32_e32 v117, 2, v109
	v_or_b32_e32 v118, 34, v109
	v_or_b32_e32 v119, 3, v109
	v_or_b32_e32 v120, 35, v109
	v_or_b32_e32 v121, 8, v109
	v_or_b32_e32 v122, 40, v109
	v_or_b32_e32 v123, 9, v109
	v_or_b32_e32 v124, 41, v109
	v_or_b32_e32 v125, 10, v109
	v_or_b32_e32 v126, 42, v109
	v_or_b32_e32 v127, 11, v109
	v_or_b32_e32 v128, 43, v109
	v_or_b32_e32 v129, 16, v109
	v_or_b32_e32 v130, 48, v109
	v_or_b32_e32 v131, 17, v109
	v_or_b32_e32 v132, 49, v109
	v_or_b32_e32 v133, 18, v109
	v_or_b32_e32 v134, 50, v109
	v_or_b32_e32 v135, 19, v109
	v_or_b32_e32 v136, 51, v109
	v_or_b32_e32 v137, 24, v109
	v_or_b32_e32 v138, 56, v109
	v_or_b32_e32 v139, 25, v109
	v_or_b32_e32 v140, 57, v109
	v_or_b32_e32 v141, 26, v109
	v_or_b32_e32 v142, 58, v109
	v_or_b32_e32 v143, 27, v109
	v_or_b32_e32 v144, 59, v109
	v_ashrrev_i32_e32 v105, 31, v104
	s_cselect_b64 s[72:73], -1, 0
	v_mov_b32_e32 v146, 0xff800000
	v_mov_b32_e32 v145, 0
	v_mov_b64_e32 v[20:21], v[66:67]
	v_mov_b64_e32 v[22:23], v[68:69]
	v_mov_b64_e32 v[24:25], v[70:71]
	v_mov_b64_e32 v[26:27], v[72:73]
	v_mov_b64_e32 v[28:29], v[74:75]
	v_mov_b64_e32 v[30:31], v[76:77]
	v_mov_b64_e32 v[32:33], v[78:79]
	s_barrier
	s_waitcnt vmcnt(4)
	v_mul_f32_e32 v34, 0x3fb8aa3b, v4
	v_mov_b64_e32 v[2:3], v[64:65]
	v_mov_b32_e32 v35, v34
	v_mov_b32_e32 v36, v34
	v_mov_b32_e32 v37, v34
	v_mov_b32_e32 v38, v34
	v_mov_b32_e32 v39, v34
	v_mov_b32_e32 v40, v34
	v_mov_b32_e32 v41, v34
	v_mov_b32_e32 v42, v34
	v_mov_b32_e32 v43, v34
	v_mov_b32_e32 v44, v34
	v_mov_b32_e32 v45, v34
	v_mov_b32_e32 v46, v34
	v_mov_b32_e32 v47, v34
	v_mov_b32_e32 v48, v34
	v_mov_b32_e32 v49, v34
	v_mov_b64_e32 v[4:5], v[66:67]
	v_mov_b64_e32 v[6:7], v[68:69]
	v_mov_b64_e32 v[8:9], v[70:71]
	v_mov_b64_e32 v[10:11], v[72:73]
	v_mov_b64_e32 v[12:13], v[74:75]
	v_mov_b64_e32 v[14:15], v[76:77]
	v_mov_b64_e32 v[16:17], v[78:79]
	s_branch .LBB0_1651

; __device__ __forceinline__ void fox_attention(const Args& a, LAS unsigned char* lds, int vcu, int G) {
;     ...
;             if (G == 256) {
;                 const int bh = vcu >> 1, s0 = 2 * (vcu & 1);
; #pragma unroll 1
;                 for (int i = 0; i < 4; ++i) attn_unit_prompt(a, lds, bh >> 4, bh & 15, (i & 1) ? s0 + (i >> 1) : 7 - s0 - (i >> 1));
.LBB0_1716:
	s_setprio 0
	v_readfirstlane_b32 s98, v0
	s_nop 3
	s_lshr_b32 s98, s98, 6
	s_cmp_ge_u32 s98, 4
	s_cbranch_scc0 .Lp10_prio_done
	s_setprio 1

; #define SEAM(k) do { if (IN(k) && IN((k) + 1)) { if ((k) == 0 && a.ph_hi < 0) cg::this_grid().sync(); xcd_barrier(xbar); } } while (0)
; __device__ __forceinline__ void xcd_barrier(const XcdBarrier& b) {
;     asm volatile("s_waitcnt vmcnt(0)" ::: "memory");
;     __syncthreads();
;     if (threadIdx.x == 0) {
;         unsigned* bar = b.bar;
;         __builtin_amdgcn_s_waitcnt(0);
;         unsigned nloc = b.st[0], nx = b.st[1];
;         if (nloc == 0u) { xcd_barrier_complete(bar, b.x, nloc, nx); b.st[0] = nloc; b.st[1] = nx; }
; __global__ void __launch_bounds__(512, 2) fwd(Args a) {
;     ...
;     SEAM(10);
.LBB0_1758:
	s_setprio 0
	s_cmp_gt_i32 s31, 11
	s_cselect_b64 s[0:1], -1, 0
	s_and_b64 s[4:5], s[4:5], s[0:1]
	s_andn2_b64 vcc, exec, s[4:5]
	s_cbranch_vccnz .LBB0_1808
	s_waitcnt vmcnt(0)
	v_cmp_eq_u32_e32 vcc, 0, v0
	s_waitcnt lgkmcnt(0)
	s_barrier
	s_and_saveexec_b64 s[4:5], vcc
	s_cbranch_execz .LBB0_1807
	v_mov_b32_e32 v2, s97
	s_waitcnt vmcnt(0) expcnt(0) lgkmcnt(0)
	ds_read_b32 v4, v2
	ds_read_b32 v2, v2 offset:4
	s_waitcnt lgkmcnt(1)
	v_cmp_ne_u32_e32 vcc, 0, v4
	s_cbranch_vccnz .LBB0_1775
	v_readlane_b32 s6, v252, 8
	v_readlane_b32 s7, v252, 9
	s_load_dwordx2 s[10:11], s[6:7], 0x4
	s_add_u32 s6, s28, 0x1000
	s_addc_u32 s7, s29, 0
	s_add_u32 s8, s28, 0x1100
	s_addc_u32 s9, s29, 0
	s_waitcnt lgkmcnt(0)
	s_mul_i32 s3, s10, s34
	s_add_u32 s10, s28, 0x1200
	s_mul_i32 s3, s3, s11
	s_addc_u32 s11, s29, 0
	s_add_u32 s14, s28, 0x1300
	s_addc_u32 s15, s29, 0
	s_mov_b32 s24, 1
	v_mov_b32_e32 v18, 0
	s_branch .LBB0_1763
